# prep_mod GEMV: touch-prefetch weight lines of k-iterations 2-4 (48 dummy loads) before the load/FMA loop to hide 3 serial HBM latencies
# baseline (speedup 1.0000x reference)
; __device__ __forceinline__ void prep_mod(Frame& F) {
;     ...
;         for (int item = F.bid; item < 2 * 96; item += F.G) {
;             const int layer = item / 96, n0 = (item % 96) * 32, kk = tid >> 5, nn = tid & 31;
;             const float* w = F.in[I_ADAW] + (size_t)layer * D * 3072 + n0 + nn;
;             float s0 = 0.f, s1 = 0.f, s2 = 0.f;
;             for (int k = kk; k < D; k += 256) { float wv[16];
; #pragma unroll
;                 for (int i = 0; i < 16; ++i) wv[i] = w[(size_t)(k + 16 * i) * 3072];
; #pragma unroll
;                 for (int i = 0; i < 16; ++i) { s0 += sc[k + 16 * i] * wv[i]; s1 += sc[D + k + 16 * i] * wv[i]; s2 += sc[2 * D + k + 16 * i] * wv[i]; } }
.LBB0_11:
	s_mul_hi_i32 s4, s14, 0x2aaaaaab
	s_lshr_b32 s5, s4, 31
	s_ashr_i32 s15, s4, 4
	s_add_i32 s15, s15, s5
	s_mul_i32 s4, s15, 0x60
	s_sub_i32 s4, s14, s4
	s_lshl_b32 s10, s4, 5
	s_ashr_i32 s11, s10, 31
	s_mul_i32 s13, s15, 0xc00000
	s_lshl_b64 s[4:5], s[10:11], 2
	s_mul_hi_i32 s12, s15, 0xc00000
	s_add_u32 s4, s13, s4
	s_addc_u32 s5, s12, s5
	v_lshl_add_u64 v[12:13], v[10:11], 0, s[4:5]
	s_mov_b64 s[98:99], 0x300000
	v_lshl_add_u64 v[92:93], v[12:13], 0, s[98:99]
	s_mov_b64 s[98:99], 0x30000
	global_load_dword v94, v[92:93], off
	v_lshl_add_u64 v[92:93], v[92:93], 0, s[98:99]
	global_load_dword v94, v[92:93], off
	v_lshl_add_u64 v[92:93], v[92:93], 0, s[98:99]
	global_load_dword v94, v[92:93], off
	v_lshl_add_u64 v[92:93], v[92:93], 0, s[98:99]
	global_load_dword v94, v[92:93], off
	v_lshl_add_u64 v[92:93], v[92:93], 0, s[98:99]
	global_load_dword v94, v[92:93], off
	v_lshl_add_u64 v[92:93], v[92:93], 0, s[98:99]
	global_load_dword v94, v[92:93], off
	v_lshl_add_u64 v[92:93], v[92:93], 0, s[98:99]
	global_load_dword v94, v[92:93], off
	v_lshl_add_u64 v[92:93], v[92:93], 0, s[98:99]
	global_load_dword v94, v[92:93], off
	v_lshl_add_u64 v[92:93], v[92:93], 0, s[98:99]
	global_load_dword v94, v[92:93], off
	v_lshl_add_u64 v[92:93], v[92:93], 0, s[98:99]
	global_load_dword v94, v[92:93], off
	v_lshl_add_u64 v[92:93], v[92:93], 0, s[98:99]
	global_load_dword v94, v[92:93], off
	v_lshl_add_u64 v[92:93], v[92:93], 0, s[98:99]
	global_load_dword v94, v[92:93], off
	v_lshl_add_u64 v[92:93], v[92:93], 0, s[98:99]
	global_load_dword v94, v[92:93], off
	v_lshl_add_u64 v[92:93], v[92:93], 0, s[98:99]
	global_load_dword v94, v[92:93], off
	v_lshl_add_u64 v[92:93], v[92:93], 0, s[98:99]
	global_load_dword v94, v[92:93], off
	v_lshl_add_u64 v[92:93], v[92:93], 0, s[98:99]
	global_load_dword v94, v[92:93], off
	v_lshl_add_u64 v[92:93], v[92:93], 0, s[98:99]
	global_load_dword v94, v[92:93], off
	v_lshl_add_u64 v[92:93], v[92:93], 0, s[98:99]
	global_load_dword v94, v[92:93], off
	v_lshl_add_u64 v[92:93], v[92:93], 0, s[98:99]
	global_load_dword v94, v[92:93], off
	v_lshl_add_u64 v[92:93], v[92:93], 0, s[98:99]
	global_load_dword v94, v[92:93], off
	v_lshl_add_u64 v[92:93], v[92:93], 0, s[98:99]
	global_load_dword v94, v[92:93], off
	v_lshl_add_u64 v[92:93], v[92:93], 0, s[98:99]
	global_load_dword v94, v[92:93], off
	v_lshl_add_u64 v[92:93], v[92:93], 0, s[98:99]
	global_load_dword v94, v[92:93], off
	v_lshl_add_u64 v[92:93], v[92:93], 0, s[98:99]
	global_load_dword v94, v[92:93], off
	v_lshl_add_u64 v[92:93], v[92:93], 0, s[98:99]
	global_load_dword v94, v[92:93], off
	v_lshl_add_u64 v[92:93], v[92:93], 0, s[98:99]
	global_load_dword v94, v[92:93], off
	v_lshl_add_u64 v[92:93], v[92:93], 0, s[98:99]
	global_load_dword v94, v[92:93], off
	v_lshl_add_u64 v[92:93], v[92:93], 0, s[98:99]
	global_load_dword v94, v[92:93], off
	v_lshl_add_u64 v[92:93], v[92:93], 0, s[98:99]
	global_load_dword v94, v[92:93], off
	v_lshl_add_u64 v[92:93], v[92:93], 0, s[98:99]
	global_load_dword v94, v[92:93], off
	v_lshl_add_u64 v[92:93], v[92:93], 0, s[98:99]
	global_load_dword v94, v[92:93], off
	v_lshl_add_u64 v[92:93], v[92:93], 0, s[98:99]
	global_load_dword v94, v[92:93], off
	v_lshl_add_u64 v[92:93], v[92:93], 0, s[98:99]
	global_load_dword v94, v[92:93], off
	v_lshl_add_u64 v[92:93], v[92:93], 0, s[98:99]
	global_load_dword v94, v[92:93], off
	v_lshl_add_u64 v[92:93], v[92:93], 0, s[98:99]
	global_load_dword v94, v[92:93], off
	v_lshl_add_u64 v[92:93], v[92:93], 0, s[98:99]
	global_load_dword v94, v[92:93], off
	v_lshl_add_u64 v[92:93], v[92:93], 0, s[98:99]
	global_load_dword v94, v[92:93], off
	v_lshl_add_u64 v[92:93], v[92:93], 0, s[98:99]
	global_load_dword v94, v[92:93], off
	v_lshl_add_u64 v[92:93], v[92:93], 0, s[98:99]
	global_load_dword v94, v[92:93], off
	v_lshl_add_u64 v[92:93], v[92:93], 0, s[98:99]
	global_load_dword v94, v[92:93], off
	v_lshl_add_u64 v[92:93], v[92:93], 0, s[98:99]
	global_load_dword v94, v[92:93], off
	v_lshl_add_u64 v[92:93], v[92:93], 0, s[98:99]
	global_load_dword v94, v[92:93], off
	v_lshl_add_u64 v[92:93], v[92:93], 0, s[98:99]
	global_load_dword v94, v[92:93], off
	v_lshl_add_u64 v[92:93], v[92:93], 0, s[98:99]
	global_load_dword v94, v[92:93], off
	v_lshl_add_u64 v[92:93], v[92:93], 0, s[98:99]
	global_load_dword v94, v[92:93], off
	v_lshl_add_u64 v[92:93], v[92:93], 0, s[98:99]
	global_load_dword v94, v[92:93], off
	v_lshl_add_u64 v[92:93], v[92:93], 0, s[98:99]
	global_load_dword v94, v[92:93], off
	v_lshl_add_u64 v[92:93], v[92:93], 0, s[98:99]
	global_load_dword v94, v[92:93], off
	v_lshl_add_u64 v[92:93], v[92:93], 0, s[98:99]
	s_mov_b64 s[12:13], 0
	v_mov_b32_e32 v34, v1
	v_mov_b32_e32 v35, v3
	v_mov_b32_e32 v36, 0
	v_mov_b32_e32 v14, 0
	v_mov_b32_e32 v15, v9
